# mode-3 GEMM epilogue: residual loads software-pipelined one block ahead via saddr+voffset into spare VGPRs, counted vmcnt(1) so stores/atomics are not drained per block
# baseline (speedup 1.0000x reference)
.LBB0_276:
	s_add_i32 s68, s23, 0xffff8000
	s_and_b64 s[48:49], s[46:47], exec
	s_cselect_b32 s23, s23, s68
	v_readlane_b32 s48, v248, 10
	v_readlane_b32 s68, v248, 8
	v_add_u32_e32 v194, s23, v225
	v_readlane_b32 s49, v248, 11
	v_readlane_b32 s69, v248, 9
	s_cselect_b32 s71, s49, s69
	s_cselect_b32 s70, s48, s68
	v_readlane_b32 s48, v248, 6
	v_readlane_b32 s68, v248, 12
	v_ashrrev_i32_e32 v195, 31, v194
	v_readlane_b32 s49, v248, 7
	v_readlane_b32 s69, v248, 13
	v_lshlrev_b64 v[144:145], 10, v[194:195]
	s_cselect_b32 s69, s69, s49
	s_cselect_b32 s68, s68, s48
	s_cmp_lg_u64 s[70:71], 0
	v_lshl_add_u64 v[196:197], v[144:145], 0, v[184:185]
	s_cselect_b64 s[48:49], -1, 0
	s_cmp_eq_u64 s[70:71], 0
	v_lshl_add_u64 v[208:209], v[196:197], 2, s[70:71]
	s_cbranch_scc1 .LBB0_473
	v_lshlrev_b32_e32 v246, 2, v196
	global_load_dwordx4 v[236:239], v246, s[70:71]
	global_load_dwordx4 v[240:243], v246, s[70:71] offset:16
	s_waitcnt vmcnt(0)
	v_mov_b32_e32 v148, v236
	v_mov_b32_e32 v149, v237
	v_mov_b32_e32 v150, v238
	v_mov_b32_e32 v151, v239
	v_mov_b32_e32 v144, v240
	v_mov_b32_e32 v145, v241
	v_mov_b32_e32 v146, v242
	v_mov_b32_e32 v147, v243
	global_load_dwordx4 v[236:239], v246, s[70:71] offset:512
	global_load_dwordx4 v[240:243], v246, s[70:71] offset:528
	s_mov_b32 s23, s81
	v_lshl_add_u64 v[210:211], v[196:197], 1, s[68:69]
	s_cbranch_execnz .LBB0_279
.LBB0_278:
	v_lshlrev_b32_e32 v246, 1, v196
	global_load_dwordx4 v[236:239], v246, s[68:69]
	s_waitcnt vmcnt(0)
	v_lshlrev_b32_e32 v148, 16, v236
	v_and_b32_e32 v149, 0xffff0000, v236
	v_lshlrev_b32_e32 v150, 16, v237
	v_and_b32_e32 v151, 0xffff0000, v237
	v_lshlrev_b32_e32 v144, 16, v238
	v_and_b32_e32 v145, 0xffff0000, v238
	v_lshlrev_b32_e32 v146, 16, v239
	v_and_b32_e32 v147, 0xffff0000, v239
	global_load_dwordx4 v[236:239], v246, s[68:69] offset:256
.LBB0_279:
	s_and_b64 s[46:47], s[46:47], exec
	v_readlane_b32 s46, v249, 58
	v_readlane_b32 s80, v249, 56
	v_readlane_b32 s47, v249, 59
	v_readlane_b32 s81, v249, 57
	s_cselect_b32 s87, s47, s81
	s_cselect_b32 s86, s46, s80
	v_ashrrev_i32_e32 v175, 31, v174
	v_lshl_add_u64 v[204:205], v[196:197], 1, s[86:87]
	v_lshlrev_b64 v[206:207], 11, v[174:175]
	v_pk_fma_f32 v[196:197], v[18:19], v[138:139], v[150:151]
	v_pk_fma_f32 v[198:199], v[16:17], v[136:137], v[148:149]
	v_pk_fma_f32 v[202:203], v[28:29], v[140:141], v[144:145]
	v_cvt_pk_bf16_f32 v144, v198, v199
	v_cvt_pk_bf16_f32 v145, v196, v197
	v_pk_fma_f32 v[200:201], v[30:31], v[142:143], v[146:147]
	v_cvt_pk_bf16_f32 v146, v202, v203
	s_and_b64 vcc, exec, s[44:45]
	v_cvt_pk_bf16_f32 v147, v200, v201
	global_store_dwordx4 v[204:205], v[144:147], off
	s_nop 1
	v_lshl_add_u64 v[144:145], s[82:83], 0, v[206:207]
	v_lshl_add_u64 v[206:207], v[184:185], 1, v[144:145]
	s_cbranch_vccnz .LBB0_281
	v_pk_mul_f32 v[146:147], v[190:191], v[196:197]
	v_pk_mul_f32 v[144:145], v[188:189], v[198:199]
	v_pk_mul_f32 v[148:149], v[192:193], v[200:201]
	v_pk_mul_f32 v[150:151], v[186:187], v[202:203]
	v_cvt_pk_bf16_f32 v144, v144, v145
	v_cvt_pk_bf16_f32 v145, v146, v147
	s_nop 0
	v_cvt_pk_bf16_f32 v146, v150, v151
	v_cvt_pk_bf16_f32 v147, v148, v149
	global_store_dwordx4 v[206:207], v[144:147], off
.LBB0_281:
	s_nop 1
	v_cndmask_b32_e64 v144, 0, 1, s[48:49]
	v_cmp_ne_u32_e64 s[46:47], 1, v144
	s_andn2_b64 vcc, exec, s[48:49]
	s_cbranch_vccnz .LBB0_474
	s_waitcnt vmcnt(1)
	v_mov_b32_e32 v148, v236
	v_mov_b32_e32 v149, v237
	v_mov_b32_e32 v150, v238
	v_mov_b32_e32 v151, v239
	v_mov_b32_e32 v144, v240
	v_mov_b32_e32 v145, v241
	v_mov_b32_e32 v146, v242
	v_mov_b32_e32 v147, v243
	v_add_u32_e32 v246, 0x10000, v246
	global_load_dwordx4 v[236:239], v246, s[70:71]
	global_load_dwordx4 v[240:243], v246, s[70:71] offset:16
	s_cbranch_execnz .LBB0_284
.LBB0_283:
	s_waitcnt vmcnt(1)
	v_lshlrev_b32_e32 v148, 16, v236
	v_and_b32_e32 v149, 0xffff0000, v236
	v_lshlrev_b32_e32 v150, 16, v237
	v_and_b32_e32 v151, 0xffff0000, v237
	v_lshlrev_b32_e32 v144, 16, v238
	v_and_b32_e32 v145, 0xffff0000, v238
	v_lshlrev_b32_e32 v146, 16, v239
	v_and_b32_e32 v147, 0xffff0000, v239
	v_add_u32_e32 v246, 0x8000, v246
	global_load_dwordx4 v[236:239], v246, s[68:69]
.LBB0_284:
	v_pk_fma_f32 v[150:151], v[26:27], v[130:131], v[150:151]
	v_pk_fma_f32 v[148:149], v[24:25], v[128:129], v[148:149]
	v_pk_fma_f32 v[146:147], v[22:23], v[134:135], v[146:147]
	v_pk_fma_f32 v[144:145], v[20:21], v[132:133], v[144:145]
	s_and_b64 vcc, exec, s[44:45]
	v_cvt_pk_bf16_f32 v208, v148, v149
	v_cvt_pk_bf16_f32 v209, v150, v151
	v_cvt_pk_bf16_f32 v210, v144, v145
	v_cvt_pk_bf16_f32 v211, v146, v147
	global_store_dwordx4 v[204:205], v[208:211], off offset:256
	s_cbranch_vccnz .LBB0_286
	s_nop 0
	v_pk_mul_f32 v[208:209], v[178:179], v[148:149]
	v_pk_mul_f32 v[210:211], v[176:177], v[144:145]
	v_pk_mul_f32 v[204:205], v[180:181], v[150:151]
	v_pk_mul_f32 v[232:233], v[182:183], v[146:147]
	v_cvt_pk_bf16_f32 v208, v208, v209
	v_cvt_pk_bf16_f32 v209, v204, v205
	v_cvt_pk_bf16_f32 v210, v210, v211
	s_nop 0
	v_cvt_pk_bf16_f32 v211, v232, v233
	global_store_dwordx4 v[206:207], v[208:211], off offset:256

.LBB0_290:
	v_or_b32_e32 v144, 16, v194
	v_ashrrev_i32_e32 v145, 31, v144
	v_lshlrev_b64 v[144:145], 10, v[144:145]
	v_lshl_add_u64 v[196:197], v[144:145], 0, v[184:185]
	s_and_b64 vcc, exec, s[46:47]
	v_lshl_add_u64 v[210:211], v[196:197], 2, s[70:71]
	s_cbranch_vccnz .LBB0_475
	s_waitcnt vmcnt(1)
	v_mov_b32_e32 v148, v236
	v_mov_b32_e32 v149, v237
	v_mov_b32_e32 v150, v238
	v_mov_b32_e32 v151, v239
	v_mov_b32_e32 v144, v240
	v_mov_b32_e32 v145, v241
	v_mov_b32_e32 v146, v242
	v_mov_b32_e32 v147, v243
	global_load_dwordx4 v[236:239], v246, s[70:71] offset:512
	global_load_dwordx4 v[240:243], v246, s[70:71] offset:528
	v_lshl_add_u64 v[208:209], v[196:197], 1, s[68:69]
	s_cbranch_execnz .LBB0_293
.LBB0_292:
	s_waitcnt vmcnt(1)
	v_lshlrev_b32_e32 v148, 16, v236
	v_and_b32_e32 v149, 0xffff0000, v236
	v_lshlrev_b32_e32 v150, 16, v237
	v_and_b32_e32 v151, 0xffff0000, v237
	v_lshlrev_b32_e32 v144, 16, v238
	v_and_b32_e32 v145, 0xffff0000, v238
	v_lshlrev_b32_e32 v146, 16, v239
	v_and_b32_e32 v147, 0xffff0000, v239
	global_load_dwordx4 v[236:239], v246, s[68:69] offset:256
.LBB0_293:
	v_lshl_add_u64 v[204:205], v[196:197], 1, s[86:87]
	v_or_b32_e32 v196, 16, v174
	v_ashrrev_i32_e32 v197, 31, v196
	v_lshlrev_b64 v[206:207], 11, v[196:197]
	v_pk_fma_f32 v[196:197], v[14:15], v[138:139], v[150:151]
	v_pk_fma_f32 v[198:199], v[12:13], v[136:137], v[148:149]
	v_pk_fma_f32 v[202:203], v[8:9], v[140:141], v[144:145]
	v_cvt_pk_bf16_f32 v144, v198, v199
	v_cvt_pk_bf16_f32 v145, v196, v197
	v_pk_fma_f32 v[200:201], v[10:11], v[142:143], v[146:147]
	v_cvt_pk_bf16_f32 v146, v202, v203
	s_and_b64 vcc, exec, s[44:45]
	v_cvt_pk_bf16_f32 v147, v200, v201
	global_store_dwordx4 v[204:205], v[144:147], off
	s_nop 1
	v_lshl_add_u64 v[144:145], s[82:83], 0, v[206:207]
	v_lshl_add_u64 v[206:207], v[184:185], 1, v[144:145]
	s_cbranch_vccnz .LBB0_295
	v_pk_mul_f32 v[146:147], v[190:191], v[196:197]
	v_pk_mul_f32 v[144:145], v[188:189], v[198:199]
	v_pk_mul_f32 v[148:149], v[192:193], v[200:201]
	v_pk_mul_f32 v[150:151], v[186:187], v[202:203]
	v_cvt_pk_bf16_f32 v144, v144, v145
	v_cvt_pk_bf16_f32 v145, v146, v147
	s_nop 0
	v_cvt_pk_bf16_f32 v146, v150, v151
	v_cvt_pk_bf16_f32 v147, v148, v149
	global_store_dwordx4 v[206:207], v[144:147], off
.LBB0_295:
	s_and_b64 vcc, exec, s[46:47]
	s_cbranch_vccnz .LBB0_476
	s_waitcnt vmcnt(1)
	v_mov_b32_e32 v148, v236
	v_mov_b32_e32 v149, v237
	v_mov_b32_e32 v150, v238
	v_mov_b32_e32 v151, v239
	v_mov_b32_e32 v144, v240
	v_mov_b32_e32 v145, v241
	v_mov_b32_e32 v146, v242
	v_mov_b32_e32 v147, v243
	v_add_u32_e32 v246, 0x10000, v246
	global_load_dwordx4 v[236:239], v246, s[70:71]
	global_load_dwordx4 v[240:243], v246, s[70:71] offset:16
	s_cbranch_execnz .LBB0_298

.LBB0_298:
	v_pk_fma_f32 v[150:151], v[6:7], v[130:131], v[150:151]
	v_pk_fma_f32 v[148:149], v[4:5], v[128:129], v[148:149]
	v_pk_fma_f32 v[146:147], v[2:3], v[134:135], v[146:147]
	v_pk_fma_f32 v[144:145], v[0:1], v[132:133], v[144:145]
	s_and_b64 vcc, exec, s[44:45]
	v_cvt_pk_bf16_f32 v208, v148, v149
	v_cvt_pk_bf16_f32 v209, v150, v151
	v_cvt_pk_bf16_f32 v210, v144, v145
	v_cvt_pk_bf16_f32 v211, v146, v147
	global_store_dwordx4 v[204:205], v[208:211], off offset:256
	s_cbranch_vccnz .LBB0_300
	s_nop 0
	v_pk_mul_f32 v[208:209], v[178:179], v[148:149]
	v_pk_mul_f32 v[210:211], v[176:177], v[144:145]
	v_pk_mul_f32 v[204:205], v[180:181], v[150:151]
	v_pk_mul_f32 v[232:233], v[182:183], v[146:147]
	v_cvt_pk_bf16_f32 v208, v208, v209
	v_cvt_pk_bf16_f32 v209, v204, v205
	v_cvt_pk_bf16_f32 v210, v210, v211
	s_nop 0
	v_cvt_pk_bf16_f32 v211, v232, v233
	global_store_dwordx4 v[206:207], v[208:211], off offset:256

.LBB0_304:
	v_or_b32_e32 v144, 32, v194
	v_ashrrev_i32_e32 v145, 31, v144
	v_lshlrev_b64 v[144:145], 10, v[144:145]
	v_lshl_add_u64 v[196:197], v[144:145], 0, v[184:185]
	s_and_b64 vcc, exec, s[46:47]
	v_lshl_add_u64 v[210:211], v[196:197], 2, s[70:71]
	s_cbranch_vccnz .LBB0_477
	s_waitcnt vmcnt(1)
	v_mov_b32_e32 v148, v236
	v_mov_b32_e32 v149, v237
	v_mov_b32_e32 v150, v238
	v_mov_b32_e32 v151, v239
	v_mov_b32_e32 v144, v240
	v_mov_b32_e32 v145, v241
	v_mov_b32_e32 v146, v242
	v_mov_b32_e32 v147, v243
	global_load_dwordx4 v[236:239], v246, s[70:71] offset:512
	global_load_dwordx4 v[240:243], v246, s[70:71] offset:528
	v_lshl_add_u64 v[208:209], v[196:197], 1, s[68:69]
	s_cbranch_execnz .LBB0_307

.LBB0_307:
	v_lshl_add_u64 v[204:205], v[196:197], 1, s[86:87]
	v_or_b32_e32 v196, 32, v174
	v_ashrrev_i32_e32 v197, 31, v196
	v_lshlrev_b64 v[206:207], 11, v[196:197]
	v_pk_fma_f32 v[196:197], v[126:127], v[138:139], v[150:151]
	v_pk_fma_f32 v[198:199], v[124:125], v[136:137], v[148:149]
	v_pk_fma_f32 v[202:203], v[120:121], v[140:141], v[144:145]
	v_cvt_pk_bf16_f32 v144, v198, v199
	v_cvt_pk_bf16_f32 v145, v196, v197
	v_pk_fma_f32 v[200:201], v[122:123], v[142:143], v[146:147]
	v_cvt_pk_bf16_f32 v146, v202, v203
	s_and_b64 vcc, exec, s[44:45]
	v_cvt_pk_bf16_f32 v147, v200, v201
	global_store_dwordx4 v[204:205], v[144:147], off
	s_nop 1
	v_lshl_add_u64 v[144:145], s[82:83], 0, v[206:207]
	v_lshl_add_u64 v[206:207], v[184:185], 1, v[144:145]
	s_cbranch_vccnz .LBB0_309
	v_pk_mul_f32 v[146:147], v[190:191], v[196:197]
	v_pk_mul_f32 v[144:145], v[188:189], v[198:199]
	v_pk_mul_f32 v[148:149], v[192:193], v[200:201]
	v_pk_mul_f32 v[150:151], v[186:187], v[202:203]
	v_cvt_pk_bf16_f32 v144, v144, v145
	v_cvt_pk_bf16_f32 v145, v146, v147
	s_nop 0
	v_cvt_pk_bf16_f32 v146, v150, v151
	v_cvt_pk_bf16_f32 v147, v148, v149
	global_store_dwordx4 v[206:207], v[144:147], off

.LBB0_312:
	v_pk_fma_f32 v[150:151], v[118:119], v[130:131], v[150:151]
	v_pk_fma_f32 v[148:149], v[116:117], v[128:129], v[148:149]
	v_pk_fma_f32 v[146:147], v[114:115], v[134:135], v[146:147]
	v_pk_fma_f32 v[144:145], v[112:113], v[132:133], v[144:145]
	s_and_b64 vcc, exec, s[44:45]
	v_cvt_pk_bf16_f32 v208, v148, v149
	v_cvt_pk_bf16_f32 v209, v150, v151
	v_cvt_pk_bf16_f32 v210, v144, v145
	v_cvt_pk_bf16_f32 v211, v146, v147
	global_store_dwordx4 v[204:205], v[208:211], off offset:256
	s_cbranch_vccnz .LBB0_314
	s_nop 0
	v_pk_mul_f32 v[208:209], v[178:179], v[148:149]
	v_pk_mul_f32 v[210:211], v[176:177], v[144:145]
	v_pk_mul_f32 v[204:205], v[180:181], v[150:151]
	v_pk_mul_f32 v[232:233], v[182:183], v[146:147]
	v_cvt_pk_bf16_f32 v208, v208, v209
	v_cvt_pk_bf16_f32 v209, v204, v205
	v_cvt_pk_bf16_f32 v210, v210, v211
	s_nop 0
	v_cvt_pk_bf16_f32 v211, v232, v233
	global_store_dwordx4 v[206:207], v[208:211], off offset:256

.LBB0_318:
	v_or_b32_e32 v144, 48, v194
	v_ashrrev_i32_e32 v145, 31, v144
	v_lshlrev_b64 v[144:145], 10, v[144:145]
	v_lshl_add_u64 v[196:197], v[144:145], 0, v[184:185]
	s_and_b64 vcc, exec, s[46:47]
	v_lshl_add_u64 v[210:211], v[196:197], 2, s[70:71]
	s_cbranch_vccnz .LBB0_479
	s_waitcnt vmcnt(1)
	v_mov_b32_e32 v148, v236
	v_mov_b32_e32 v149, v237
	v_mov_b32_e32 v150, v238
	v_mov_b32_e32 v151, v239
	v_mov_b32_e32 v144, v240
	v_mov_b32_e32 v145, v241
	v_mov_b32_e32 v146, v242
	v_mov_b32_e32 v147, v243
	global_load_dwordx4 v[236:239], v246, s[70:71] offset:512
	global_load_dwordx4 v[240:243], v246, s[70:71] offset:528
	v_lshl_add_u64 v[208:209], v[196:197], 1, s[68:69]
	s_cbranch_execnz .LBB0_321

.LBB0_321:
	v_lshl_add_u64 v[204:205], v[196:197], 1, s[86:87]
	v_or_b32_e32 v196, 48, v174
	v_ashrrev_i32_e32 v197, 31, v196
	v_lshlrev_b64 v[206:207], 11, v[196:197]
	v_pk_fma_f32 v[196:197], v[110:111], v[138:139], v[150:151]
	v_pk_fma_f32 v[198:199], v[108:109], v[136:137], v[148:149]
	v_pk_fma_f32 v[202:203], v[104:105], v[140:141], v[144:145]
	v_cvt_pk_bf16_f32 v144, v198, v199
	v_cvt_pk_bf16_f32 v145, v196, v197
	v_pk_fma_f32 v[200:201], v[106:107], v[142:143], v[146:147]
	v_cvt_pk_bf16_f32 v146, v202, v203
	s_and_b64 vcc, exec, s[44:45]
	v_cvt_pk_bf16_f32 v147, v200, v201
	global_store_dwordx4 v[204:205], v[144:147], off
	s_nop 1
	v_lshl_add_u64 v[144:145], s[82:83], 0, v[206:207]
	v_lshl_add_u64 v[206:207], v[184:185], 1, v[144:145]
	s_cbranch_vccnz .LBB0_323
	v_pk_mul_f32 v[146:147], v[190:191], v[196:197]
	v_pk_mul_f32 v[144:145], v[188:189], v[198:199]
	v_pk_mul_f32 v[148:149], v[192:193], v[200:201]
	v_pk_mul_f32 v[150:151], v[186:187], v[202:203]
	v_cvt_pk_bf16_f32 v144, v144, v145
	v_cvt_pk_bf16_f32 v145, v146, v147
	s_nop 0
	v_cvt_pk_bf16_f32 v146, v150, v151
	v_cvt_pk_bf16_f32 v147, v148, v149
	global_store_dwordx4 v[206:207], v[144:147], off
.LBB0_323:
	s_and_b64 vcc, exec, s[46:47]
	s_cbranch_vccnz .LBB0_480
	s_waitcnt vmcnt(1)
	v_mov_b32_e32 v148, v236
	v_mov_b32_e32 v149, v237
	v_mov_b32_e32 v150, v238
	v_mov_b32_e32 v151, v239
	v_mov_b32_e32 v144, v240
	v_mov_b32_e32 v145, v241
	v_mov_b32_e32 v146, v242
	v_mov_b32_e32 v147, v243
	v_add_u32_e32 v246, 0x50000, v246
	global_load_dwordx4 v[236:239], v246, s[70:71]
	global_load_dwordx4 v[240:243], v246, s[70:71] offset:16
	s_cbranch_execnz .LBB0_326
.LBB0_325:
	s_waitcnt vmcnt(1)
	v_lshlrev_b32_e32 v148, 16, v236
	v_and_b32_e32 v149, 0xffff0000, v236
	v_lshlrev_b32_e32 v150, 16, v237
	v_and_b32_e32 v151, 0xffff0000, v237
	v_lshlrev_b32_e32 v144, 16, v238
	v_and_b32_e32 v145, 0xffff0000, v238
	v_lshlrev_b32_e32 v146, 16, v239
	v_and_b32_e32 v147, 0xffff0000, v239
	v_add_u32_e32 v246, 0x28000, v246
	global_load_dwordx4 v[236:239], v246, s[68:69]
.LBB0_326:
	v_pk_fma_f32 v[150:151], v[102:103], v[130:131], v[150:151]
	v_pk_fma_f32 v[148:149], v[100:101], v[128:129], v[148:149]
	v_pk_fma_f32 v[146:147], v[98:99], v[134:135], v[146:147]
	v_pk_fma_f32 v[144:145], v[96:97], v[132:133], v[144:145]
	s_and_b64 vcc, exec, s[44:45]
	v_cvt_pk_bf16_f32 v208, v148, v149
	v_cvt_pk_bf16_f32 v209, v150, v151
	v_cvt_pk_bf16_f32 v210, v144, v145
	v_cvt_pk_bf16_f32 v211, v146, v147
	global_store_dwordx4 v[204:205], v[208:211], off offset:256
	s_cbranch_vccnz .LBB0_328
	s_nop 0
	v_pk_mul_f32 v[208:209], v[178:179], v[148:149]
	v_pk_mul_f32 v[210:211], v[176:177], v[144:145]
	v_pk_mul_f32 v[204:205], v[180:181], v[150:151]
	v_pk_mul_f32 v[232:233], v[182:183], v[146:147]
	v_cvt_pk_bf16_f32 v208, v208, v209
	v_cvt_pk_bf16_f32 v209, v204, v205
	v_cvt_pk_bf16_f32 v210, v210, v211
	s_nop 0
	v_cvt_pk_bf16_f32 v211, v232, v233
	global_store_dwordx4 v[206:207], v[208:211], off offset:256

.LBB0_332:
	v_lshlrev_b64 v[144:145], 10, v[194:195]
	v_lshl_add_u64 v[144:145], v[144:145], 0, v[184:185]
	s_mov_b64 s[80:81], 0x20000
	v_lshl_add_u64 v[196:197], v[144:145], 0, s[80:81]
	s_and_b64 vcc, exec, s[46:47]
	v_lshl_add_u64 v[210:211], v[196:197], 2, s[70:71]
	s_cbranch_vccnz .LBB0_481
	s_waitcnt vmcnt(1)
	v_mov_b32_e32 v148, v236
	v_mov_b32_e32 v149, v237
	v_mov_b32_e32 v150, v238
	v_mov_b32_e32 v151, v239
	v_mov_b32_e32 v144, v240
	v_mov_b32_e32 v145, v241
	v_mov_b32_e32 v146, v242
	v_mov_b32_e32 v147, v243
	global_load_dwordx4 v[236:239], v246, s[70:71] offset:512
	global_load_dwordx4 v[240:243], v246, s[70:71] offset:528
	v_lshl_add_u64 v[208:209], v[196:197], 1, s[68:69]
	s_cbranch_execnz .LBB0_335

.LBB0_335:
	v_lshl_add_u64 v[204:205], v[196:197], 1, s[86:87]
	v_lshlrev_b64 v[196:197], 11, v[174:175]
	s_mov_b64 s[80:81], 0x40000
	v_lshl_add_u64 v[206:207], v[196:197], 0, s[80:81]
	v_pk_fma_f32 v[196:197], v[94:95], v[138:139], v[150:151]
	v_pk_fma_f32 v[198:199], v[92:93], v[136:137], v[148:149]
	v_pk_fma_f32 v[202:203], v[88:89], v[140:141], v[144:145]
	v_cvt_pk_bf16_f32 v144, v198, v199
	v_cvt_pk_bf16_f32 v145, v196, v197
	v_pk_fma_f32 v[200:201], v[90:91], v[142:143], v[146:147]
	v_cvt_pk_bf16_f32 v146, v202, v203
	s_and_b64 vcc, exec, s[44:45]
	v_cvt_pk_bf16_f32 v147, v200, v201
	global_store_dwordx4 v[204:205], v[144:147], off
	s_nop 1
	v_lshl_add_u64 v[144:145], s[82:83], 0, v[206:207]
	v_lshl_add_u64 v[206:207], v[184:185], 1, v[144:145]
	s_cbranch_vccnz .LBB0_337
	v_pk_mul_f32 v[146:147], v[190:191], v[196:197]
	v_pk_mul_f32 v[144:145], v[188:189], v[198:199]
	v_pk_mul_f32 v[148:149], v[192:193], v[200:201]
	v_pk_mul_f32 v[150:151], v[186:187], v[202:203]
	v_cvt_pk_bf16_f32 v144, v144, v145
	v_cvt_pk_bf16_f32 v145, v146, v147
	s_nop 0
	v_cvt_pk_bf16_f32 v146, v150, v151
	v_cvt_pk_bf16_f32 v147, v148, v149
	global_store_dwordx4 v[206:207], v[144:147], off

.LBB0_340:
	v_pk_fma_f32 v[150:151], v[86:87], v[130:131], v[150:151]
	v_pk_fma_f32 v[148:149], v[84:85], v[128:129], v[148:149]
	v_pk_fma_f32 v[146:147], v[82:83], v[134:135], v[146:147]
	v_pk_fma_f32 v[144:145], v[80:81], v[132:133], v[144:145]
	s_and_b64 vcc, exec, s[44:45]
	v_cvt_pk_bf16_f32 v208, v148, v149
	v_cvt_pk_bf16_f32 v209, v150, v151
	v_cvt_pk_bf16_f32 v210, v144, v145
	v_cvt_pk_bf16_f32 v211, v146, v147
	global_store_dwordx4 v[204:205], v[208:211], off offset:256
	s_cbranch_vccnz .LBB0_342
	s_nop 0
	v_pk_mul_f32 v[208:209], v[178:179], v[148:149]
	v_pk_mul_f32 v[210:211], v[176:177], v[144:145]
	v_pk_mul_f32 v[204:205], v[180:181], v[150:151]
	v_pk_mul_f32 v[232:233], v[182:183], v[146:147]
	v_cvt_pk_bf16_f32 v208, v208, v209
	v_cvt_pk_bf16_f32 v209, v204, v205
	v_cvt_pk_bf16_f32 v210, v210, v211
	s_nop 0
	v_cvt_pk_bf16_f32 v211, v232, v233
	global_store_dwordx4 v[206:207], v[208:211], off offset:256

.LBB0_346:
	v_lshlrev_b64 v[144:145], 10, v[194:195]
	v_lshl_add_u64 v[144:145], v[144:145], 0, v[184:185]
	s_mov_b64 s[80:81], 0x24000
	v_lshl_add_u64 v[196:197], v[144:145], 0, s[80:81]
	s_and_b64 vcc, exec, s[46:47]
	v_lshl_add_u64 v[210:211], v[196:197], 2, s[70:71]
	s_cbranch_vccnz .LBB0_483
	s_waitcnt vmcnt(1)
	v_mov_b32_e32 v148, v236
	v_mov_b32_e32 v149, v237
	v_mov_b32_e32 v150, v238
	v_mov_b32_e32 v151, v239
	v_mov_b32_e32 v144, v240
	v_mov_b32_e32 v145, v241
	v_mov_b32_e32 v146, v242
	v_mov_b32_e32 v147, v243
	global_load_dwordx4 v[236:239], v246, s[70:71] offset:512
	global_load_dwordx4 v[240:243], v246, s[70:71] offset:528
	v_lshl_add_u64 v[208:209], v[196:197], 1, s[68:69]
	s_cbranch_execnz .LBB0_349

.LBB0_349:
	v_lshl_add_u64 v[204:205], v[196:197], 1, s[86:87]
	v_lshlrev_b64 v[196:197], 11, v[174:175]
	s_mov_b64 s[80:81], 0x48000
	v_lshl_add_u64 v[206:207], v[196:197], 0, s[80:81]
	v_pk_fma_f32 v[196:197], v[78:79], v[138:139], v[150:151]
	v_pk_fma_f32 v[198:199], v[76:77], v[136:137], v[148:149]
	v_pk_fma_f32 v[202:203], v[72:73], v[140:141], v[144:145]
	v_cvt_pk_bf16_f32 v144, v198, v199
	v_cvt_pk_bf16_f32 v145, v196, v197
	v_pk_fma_f32 v[200:201], v[74:75], v[142:143], v[146:147]
	v_cvt_pk_bf16_f32 v146, v202, v203
	s_and_b64 vcc, exec, s[44:45]
	v_cvt_pk_bf16_f32 v147, v200, v201
	global_store_dwordx4 v[204:205], v[144:147], off
	s_nop 1
	v_lshl_add_u64 v[144:145], s[82:83], 0, v[206:207]
	v_lshl_add_u64 v[206:207], v[184:185], 1, v[144:145]
	s_cbranch_vccnz .LBB0_351
	v_pk_mul_f32 v[146:147], v[190:191], v[196:197]
	v_pk_mul_f32 v[144:145], v[188:189], v[198:199]
	v_pk_mul_f32 v[148:149], v[192:193], v[200:201]
	v_pk_mul_f32 v[150:151], v[186:187], v[202:203]
	v_cvt_pk_bf16_f32 v144, v144, v145
	v_cvt_pk_bf16_f32 v145, v146, v147
	s_nop 0
	v_cvt_pk_bf16_f32 v146, v150, v151
	v_cvt_pk_bf16_f32 v147, v148, v149
	global_store_dwordx4 v[206:207], v[144:147], off

.LBB0_354:
	v_pk_fma_f32 v[150:151], v[70:71], v[130:131], v[150:151]
	v_pk_fma_f32 v[148:149], v[68:69], v[128:129], v[148:149]
	v_pk_fma_f32 v[146:147], v[66:67], v[134:135], v[146:147]
	v_pk_fma_f32 v[144:145], v[64:65], v[132:133], v[144:145]
	s_and_b64 vcc, exec, s[44:45]
	v_cvt_pk_bf16_f32 v208, v148, v149
	v_cvt_pk_bf16_f32 v209, v150, v151
	v_cvt_pk_bf16_f32 v210, v144, v145
	v_cvt_pk_bf16_f32 v211, v146, v147
	global_store_dwordx4 v[204:205], v[208:211], off offset:256
	s_cbranch_vccnz .LBB0_356
	s_nop 0
	v_pk_mul_f32 v[208:209], v[178:179], v[148:149]
	v_pk_mul_f32 v[210:211], v[176:177], v[144:145]
	v_pk_mul_f32 v[204:205], v[180:181], v[150:151]
	v_pk_mul_f32 v[232:233], v[182:183], v[146:147]
	v_cvt_pk_bf16_f32 v208, v208, v209
	v_cvt_pk_bf16_f32 v209, v204, v205
	v_cvt_pk_bf16_f32 v210, v210, v211
	s_nop 0
	v_cvt_pk_bf16_f32 v211, v232, v233
	global_store_dwordx4 v[206:207], v[208:211], off offset:256

.LBB0_360:
	v_lshlrev_b64 v[144:145], 10, v[194:195]
	v_lshl_add_u64 v[144:145], v[144:145], 0, v[184:185]
	s_mov_b64 s[80:81], 0x28000
	v_lshl_add_u64 v[196:197], v[144:145], 0, s[80:81]
	s_and_b64 vcc, exec, s[46:47]
	v_lshl_add_u64 v[210:211], v[196:197], 2, s[70:71]
	s_cbranch_vccnz .LBB0_485
	s_waitcnt vmcnt(1)
	v_mov_b32_e32 v148, v236
	v_mov_b32_e32 v149, v237
	v_mov_b32_e32 v150, v238
	v_mov_b32_e32 v151, v239
	v_mov_b32_e32 v144, v240
	v_mov_b32_e32 v145, v241
	v_mov_b32_e32 v146, v242
	v_mov_b32_e32 v147, v243
	global_load_dwordx4 v[236:239], v246, s[70:71] offset:512
	global_load_dwordx4 v[240:243], v246, s[70:71] offset:528
	v_lshl_add_u64 v[208:209], v[196:197], 1, s[68:69]
	s_cbranch_execnz .LBB0_363

.LBB0_363:
	v_lshl_add_u64 v[204:205], v[196:197], 1, s[86:87]
	v_lshlrev_b64 v[196:197], 11, v[174:175]
	s_mov_b64 s[80:81], 0x50000
	v_lshl_add_u64 v[206:207], v[196:197], 0, s[80:81]
	v_pk_fma_f32 v[196:197], v[62:63], v[138:139], v[150:151]
	v_pk_fma_f32 v[198:199], v[60:61], v[136:137], v[148:149]
	v_pk_fma_f32 v[202:203], v[56:57], v[140:141], v[144:145]
	v_cvt_pk_bf16_f32 v144, v198, v199
	v_cvt_pk_bf16_f32 v145, v196, v197
	v_pk_fma_f32 v[200:201], v[58:59], v[142:143], v[146:147]
	v_cvt_pk_bf16_f32 v146, v202, v203
	s_and_b64 vcc, exec, s[44:45]
	v_cvt_pk_bf16_f32 v147, v200, v201
	global_store_dwordx4 v[204:205], v[144:147], off
	s_nop 1
	v_lshl_add_u64 v[144:145], s[82:83], 0, v[206:207]
	v_lshl_add_u64 v[206:207], v[184:185], 1, v[144:145]
	s_cbranch_vccnz .LBB0_365
	v_pk_mul_f32 v[146:147], v[190:191], v[196:197]
	v_pk_mul_f32 v[144:145], v[188:189], v[198:199]
	v_pk_mul_f32 v[148:149], v[192:193], v[200:201]
	v_pk_mul_f32 v[150:151], v[186:187], v[202:203]
	v_cvt_pk_bf16_f32 v144, v144, v145
	v_cvt_pk_bf16_f32 v145, v146, v147
	s_nop 0
	v_cvt_pk_bf16_f32 v146, v150, v151
	v_cvt_pk_bf16_f32 v147, v148, v149
	global_store_dwordx4 v[206:207], v[144:147], off

.LBB0_368:
	v_pk_fma_f32 v[150:151], v[54:55], v[130:131], v[150:151]
	v_pk_fma_f32 v[148:149], v[52:53], v[128:129], v[148:149]
	v_pk_fma_f32 v[146:147], v[50:51], v[134:135], v[146:147]
	v_pk_fma_f32 v[144:145], v[48:49], v[132:133], v[144:145]
	s_and_b64 vcc, exec, s[44:45]
	v_cvt_pk_bf16_f32 v208, v148, v149
	v_cvt_pk_bf16_f32 v209, v150, v151
	v_cvt_pk_bf16_f32 v210, v144, v145
	v_cvt_pk_bf16_f32 v211, v146, v147
	global_store_dwordx4 v[204:205], v[208:211], off offset:256
	s_cbranch_vccnz .LBB0_370
	s_nop 0
	v_pk_mul_f32 v[208:209], v[178:179], v[148:149]
	v_pk_mul_f32 v[210:211], v[176:177], v[144:145]
	v_pk_mul_f32 v[204:205], v[180:181], v[150:151]
	v_pk_mul_f32 v[232:233], v[182:183], v[146:147]
	v_cvt_pk_bf16_f32 v208, v208, v209
	v_cvt_pk_bf16_f32 v209, v204, v205
	v_cvt_pk_bf16_f32 v210, v210, v211
	s_nop 0
	v_cvt_pk_bf16_f32 v211, v232, v233
	global_store_dwordx4 v[206:207], v[208:211], off offset:256

.LBB0_374:
	v_lshlrev_b64 v[144:145], 10, v[194:195]
	v_lshl_add_u64 v[144:145], v[144:145], 0, v[184:185]
	s_mov_b64 s[80:81], 0x2c000
	v_lshl_add_u64 v[194:195], v[144:145], 0, s[80:81]
	s_and_b64 vcc, exec, s[46:47]
	v_lshl_add_u64 v[196:197], v[194:195], 2, s[70:71]
	s_cbranch_vccnz .LBB0_487
	s_waitcnt vmcnt(1)
	v_mov_b32_e32 v148, v236
	v_mov_b32_e32 v149, v237
	v_mov_b32_e32 v150, v238
	v_mov_b32_e32 v151, v239
	v_mov_b32_e32 v144, v240
	v_mov_b32_e32 v145, v241
	v_mov_b32_e32 v146, v242
	v_mov_b32_e32 v147, v243
	global_load_dwordx4 v[236:239], v246, s[70:71] offset:512
	global_load_dwordx4 v[240:243], v246, s[70:71] offset:528
	s_mov_b32 s81, s23
	v_lshl_add_u64 v[198:199], v[194:195], 1, s[68:69]
	s_cbranch_execnz .LBB0_377

.LBB0_377:
	v_lshlrev_b64 v[200:201], 11, v[174:175]
	s_mov_b64 s[68:69], 0x58000
	v_lshl_add_u64 v[194:195], v[194:195], 1, s[86:87]
	v_lshl_add_u64 v[200:201], v[200:201], 0, s[68:69]
	v_pk_fma_f32 v[150:151], v[46:47], v[138:139], v[150:151]
	v_pk_fma_f32 v[148:149], v[44:45], v[136:137], v[148:149]
	v_pk_fma_f32 v[146:147], v[42:43], v[142:143], v[146:147]
	v_cvt_pk_bf16_f32 v136, v148, v149
	v_cvt_pk_bf16_f32 v137, v150, v151
	v_pk_fma_f32 v[144:145], v[40:41], v[140:141], v[144:145]
	s_and_b64 vcc, exec, s[44:45]
	v_cvt_pk_bf16_f32 v138, v144, v145
	v_cvt_pk_bf16_f32 v139, v146, v147
	global_store_dwordx4 v[194:195], v[136:139], off
	s_nop 1
	v_lshl_add_u64 v[136:137], s[82:83], 0, v[200:201]
	v_lshl_add_u64 v[184:185], v[184:185], 1, v[136:137]
	s_cbranch_vccnz .LBB0_379
	v_pk_mul_f32 v[138:139], v[190:191], v[150:151]
	v_pk_mul_f32 v[136:137], v[188:189], v[148:149]
	v_pk_mul_f32 v[140:141], v[192:193], v[146:147]
	v_pk_mul_f32 v[142:143], v[186:187], v[144:145]
	v_cvt_pk_bf16_f32 v136, v136, v137
	v_cvt_pk_bf16_f32 v137, v138, v139
	s_nop 0
	v_cvt_pk_bf16_f32 v138, v142, v143
	v_cvt_pk_bf16_f32 v139, v140, v141
	global_store_dwordx4 v[184:185], v[136:139], off
.LBB0_379:
	s_and_b64 vcc, exec, s[46:47]
	s_cbranch_vccnz .LBB0_488
	s_waitcnt vmcnt(1)
	v_mov_b32_e32 v140, v236
	v_mov_b32_e32 v141, v237
	v_mov_b32_e32 v142, v238
	v_mov_b32_e32 v143, v239
	v_mov_b32_e32 v136, v240
	v_mov_b32_e32 v137, v241
	v_mov_b32_e32 v138, v242
	v_mov_b32_e32 v139, v243
	s_cbranch_execnz .LBB0_382
.LBB0_381:
	s_waitcnt vmcnt(1)
	v_lshlrev_b32_e32 v140, 16, v236
	v_and_b32_e32 v141, 0xffff0000, v236
	v_lshlrev_b32_e32 v142, 16, v237
	v_and_b32_e32 v143, 0xffff0000, v237
	v_lshlrev_b32_e32 v136, 16, v238
	v_and_b32_e32 v137, 0xffff0000, v238
	v_lshlrev_b32_e32 v138, 16, v239
	v_and_b32_e32 v139, 0xffff0000, v239
.LBB0_382:
	v_pk_fma_f32 v[130:131], v[38:39], v[130:131], v[142:143]
	v_pk_fma_f32 v[128:129], v[36:37], v[128:129], v[140:141]
	v_pk_fma_f32 v[134:135], v[34:35], v[134:135], v[138:139]
	v_pk_fma_f32 v[132:133], v[32:33], v[132:133], v[136:137]
	s_and_b64 vcc, exec, s[44:45]
	v_cvt_pk_bf16_f32 v136, v128, v129
	v_cvt_pk_bf16_f32 v137, v130, v131
	v_cvt_pk_bf16_f32 v138, v132, v133
	v_cvt_pk_bf16_f32 v139, v134, v135
	global_store_dwordx4 v[194:195], v[136:139], off offset:256
	s_cbranch_vccnz .LBB0_384
	s_nop 0
	v_pk_mul_f32 v[138:139], v[180:181], v[130:131]
	v_pk_mul_f32 v[136:137], v[178:179], v[128:129]
	v_pk_mul_f32 v[140:141], v[182:183], v[134:135]
	v_pk_mul_f32 v[142:143], v[176:177], v[132:133]
	v_cvt_pk_bf16_f32 v136, v136, v137
	v_cvt_pk_bf16_f32 v137, v138, v139
	s_nop 0
	v_cvt_pk_bf16_f32 v138, v142, v143
	v_cvt_pk_bf16_f32 v139, v140, v141
	global_store_dwordx4 v[184:185], v[136:139], off offset:256
